# phase-4 out_proj GEMM K-loop rewritten by hand: 8-phase LDS-DMA pipeline (global_load_lds, swizzled LDS, 16x16x32 MFMA, counted vmcnt, staggered wave groups), accumulators converted to 32x32 layout wi
# speedup vs baseline: 1.0171x; 1.0171x over previous
.LBB0_514:
	s_ashr_i32 s28, s1, 2
	s_ashr_i32 s29, s28, 31
	s_and_b32 s42, s1, 3
	v_lshrrev_b32_e32 v212, 6, v208
	v_and_b32_e32 v213, 63, v208
	v_readfirstlane_b32 s98, v212
	v_and_b32_e32 v214, 3, v213
	v_bfe_u32 v215, v213, 2, 1
	v_lshl_or_b32 v214, v215, 3, v214
	v_bfe_u32 v215, v213, 3, 1
	v_lshl_or_b32 v214, v215, 2, v214
	s_and_b32 s2, s98, 1
	s_lshr_b32 s100, s98, 2
	s_lshl_b32 s99, s98, 10
	v_lshrrev_b32_e32 v215, 4, v213
	v_bfe_u32 v216, v214, 1, 3
	v_xor_b32_e32 v216, v215, v216
	v_lshlrev_b32_e32 v216, 4, v216
	v_lshl_add_u32 v214, s2, 6, v214
	v_lshl_add_u32 v184, v214, 7, v216
	v_xor_b32_e32 v187, 64, v184
	v_add_u32_e32 v186, 0x10000, v184
	v_add_u32_e32 v196, 0x10000, v187
	v_bfe_u32 v216, v213, 1, 3
	v_xor_b32_e32 v216, v215, v216
	v_lshlrev_b32_e32 v216, 4, v216
	v_and_b32_e32 v214, 15, v213
	s_lshr_b32 s101, s98, 1
	v_lshl_add_u32 v214, s101, 5, v214
	v_lshl_add_u32 v197, v214, 7, v216
	v_add_u32_e32 v197, 0x8000, v197
	v_xor_b32_e32 v199, 64, v197
	v_add_u32_e32 v198, 0x10000, v197
	v_add_u32_e32 v200, 0x10000, v199
	v_lshl_add_u32 v216, s2, 2, v215
	v_and_b32_e32 v214, 7, v213
	v_xor_b32_e32 v216, v214, v216
	v_lshlrev_b32_e32 v216, 4, v216
	v_lshrrev_b32_e32 v214, 3, v213
	v_lshl_add_u32 v215, s98, 3, v214
	v_lshl_add_u32 v201, v215, 12, v216
	v_add_u32_e32 v202, 0x80000, v201
	v_add_u32_e32 v203, 0x40000, v201
	v_add_u32_e32 v204, 0xc0000, v201
	s_and_b32 s101, s98, 3
	s_lshl_b32 s101, s101, 3
	s_lshl_b32 s2, s100, 6
	s_add_u32 s101, s101, s2
	v_add_u32_e32 v215, s101, v214
	v_lshl_add_u32 v205, v215, 12, v216
	v_add_u32_e32 v206, 0x80000, v205
	v_add_u32_e32 v210, 0x20000, v205
	v_add_u32_e32 v211, 0xa0000, v205
	s_lshl_b64 s[44:45], s[28:29], 20
	s_add_u32 s44, s61, s44
	s_addc_u32 s45, s62, s45
	s_lshl_b32 s2, s42, 20
	s_add_u32 s46, s30, s2
	s_addc_u32 s47, s31, 0
	v_mov_b32_e32 v112, 0
	v_mov_b32_e32 v113, 0
	v_mov_b32_e32 v114, 0
	v_mov_b32_e32 v115, 0
	v_mov_b32_e32 v116, 0
	v_mov_b32_e32 v117, 0
	v_mov_b32_e32 v118, 0
	v_mov_b32_e32 v119, 0
	v_mov_b32_e32 v120, 0
	v_mov_b32_e32 v121, 0
	v_mov_b32_e32 v122, 0
	v_mov_b32_e32 v123, 0
	v_mov_b32_e32 v124, 0
	v_mov_b32_e32 v125, 0
	v_mov_b32_e32 v126, 0
	v_mov_b32_e32 v127, 0
	v_mov_b32_e32 v96, 0
	v_mov_b32_e32 v97, 0
	v_mov_b32_e32 v98, 0
	v_mov_b32_e32 v99, 0
	v_mov_b32_e32 v100, 0
	v_mov_b32_e32 v101, 0
	v_mov_b32_e32 v102, 0
	v_mov_b32_e32 v103, 0
	v_mov_b32_e32 v104, 0
	v_mov_b32_e32 v105, 0
	v_mov_b32_e32 v106, 0
	v_mov_b32_e32 v107, 0
	v_mov_b32_e32 v108, 0
	v_mov_b32_e32 v109, 0
	v_mov_b32_e32 v110, 0
	v_mov_b32_e32 v111, 0
	v_mov_b32_e32 v64, 0
	v_mov_b32_e32 v65, 0
	v_mov_b32_e32 v66, 0
	v_mov_b32_e32 v67, 0
	v_mov_b32_e32 v68, 0
	v_mov_b32_e32 v69, 0
	v_mov_b32_e32 v70, 0
	v_mov_b32_e32 v71, 0
	v_mov_b32_e32 v72, 0
	v_mov_b32_e32 v73, 0
	v_mov_b32_e32 v74, 0
	v_mov_b32_e32 v75, 0
	v_mov_b32_e32 v76, 0
	v_mov_b32_e32 v77, 0
	v_mov_b32_e32 v78, 0
	v_mov_b32_e32 v79, 0
	v_mov_b32_e32 v80, 0
	v_mov_b32_e32 v81, 0
	v_mov_b32_e32 v82, 0
	v_mov_b32_e32 v83, 0
	v_mov_b32_e32 v84, 0
	v_mov_b32_e32 v85, 0
	v_mov_b32_e32 v86, 0
	v_mov_b32_e32 v87, 0
	v_mov_b32_e32 v88, 0
	v_mov_b32_e32 v89, 0
	v_mov_b32_e32 v90, 0
	v_mov_b32_e32 v91, 0
	v_mov_b32_e32 v92, 0
	v_mov_b32_e32 v93, 0
	v_mov_b32_e32 v94, 0
	v_mov_b32_e32 v95, 0
	v_mov_b32_e32 v48, 0
	v_mov_b32_e32 v49, 0
	v_mov_b32_e32 v50, 0
	v_mov_b32_e32 v51, 0
	v_mov_b32_e32 v52, 0
	v_mov_b32_e32 v53, 0
	v_mov_b32_e32 v54, 0
	v_mov_b32_e32 v55, 0
	v_mov_b32_e32 v56, 0
	v_mov_b32_e32 v57, 0
	v_mov_b32_e32 v58, 0
	v_mov_b32_e32 v59, 0
	v_mov_b32_e32 v60, 0
	v_mov_b32_e32 v61, 0
	v_mov_b32_e32 v62, 0
	v_mov_b32_e32 v63, 0
	v_mov_b32_e32 v32, 0
	v_mov_b32_e32 v33, 0
	v_mov_b32_e32 v34, 0
	v_mov_b32_e32 v35, 0
	v_mov_b32_e32 v36, 0
	v_mov_b32_e32 v37, 0
	v_mov_b32_e32 v38, 0
	v_mov_b32_e32 v39, 0
	v_mov_b32_e32 v40, 0
	v_mov_b32_e32 v41, 0
	v_mov_b32_e32 v42, 0
	v_mov_b32_e32 v43, 0
	v_mov_b32_e32 v44, 0
	v_mov_b32_e32 v45, 0
	v_mov_b32_e32 v46, 0
	v_mov_b32_e32 v47, 0
	v_mov_b32_e32 v16, 0
	v_mov_b32_e32 v17, 0
	v_mov_b32_e32 v18, 0
	v_mov_b32_e32 v19, 0
	v_mov_b32_e32 v20, 0
	v_mov_b32_e32 v21, 0
	v_mov_b32_e32 v22, 0
	v_mov_b32_e32 v23, 0
	v_mov_b32_e32 v24, 0
	v_mov_b32_e32 v25, 0
	v_mov_b32_e32 v26, 0
	v_mov_b32_e32 v27, 0
	v_mov_b32_e32 v28, 0
	v_mov_b32_e32 v29, 0
	v_mov_b32_e32 v30, 0
	v_mov_b32_e32 v31, 0
	v_mov_b32_e32 v0, 0
	v_mov_b32_e32 v1, 0
	v_mov_b32_e32 v2, 0
	v_mov_b32_e32 v3, 0
	v_mov_b32_e32 v4, 0
	v_mov_b32_e32 v5, 0
	v_mov_b32_e32 v6, 0
	v_mov_b32_e32 v7, 0
	v_mov_b32_e32 v8, 0
	v_mov_b32_e32 v9, 0
	v_mov_b32_e32 v10, 0
	v_mov_b32_e32 v11, 0
	v_mov_b32_e32 v12, 0
	v_mov_b32_e32 v13, 0
	v_mov_b32_e32 v14, 0
	v_mov_b32_e32 v15, 0
	s_add_u32 m0, s99, 0x8000
	s_nop 0
	global_load_lds_dwordx4 v205, s[44:45]
	s_add_u32 m0, s99, 0xa000
	s_nop 0
	global_load_lds_dwordx4 v206, s[44:45]
	s_add_u32 m0, s99, 0x0
	s_nop 0
	global_load_lds_dwordx4 v201, s[46:47]
	s_add_u32 m0, s99, 0x2000
	s_nop 0
	global_load_lds_dwordx4 v202, s[46:47]
	s_add_u32 m0, s99, 0xc000
	s_nop 0
	global_load_lds_dwordx4 v210, s[44:45]
	s_add_u32 m0, s99, 0xe000
	s_nop 0
	global_load_lds_dwordx4 v211, s[44:45]
	s_add_u32 s44, s44, 0x80
	s_addc_u32 s45, s45, 0
	s_add_u32 m0, s99, 0x4000
	s_nop 0
	global_load_lds_dwordx4 v203, s[46:47]
	s_add_u32 m0, s99, 0x6000
	s_nop 0
	global_load_lds_dwordx4 v204, s[46:47]
	s_add_u32 s46, s46, 0x80
	s_addc_u32 s47, s47, 0
	s_cmp_eq_u32 s100, 0
	s_cbranch_scc1 .Lg8_p4_pg0
	s_barrier
.Lg8_p4_pg0:
	s_waitcnt vmcnt(4)
	s_barrier
	s_add_u32 m0, s99, 0x18000
	s_nop 0
	global_load_lds_dwordx4 v205, s[44:45]
	s_add_u32 m0, s99, 0x1a000
	s_nop 0
	global_load_lds_dwordx4 v206, s[44:45]
	s_add_u32 m0, s99, 0x10000
	s_nop 0
	global_load_lds_dwordx4 v201, s[46:47]
	s_add_u32 m0, s99, 0x12000
	s_nop 0
	global_load_lds_dwordx4 v202, s[46:47]
	s_add_u32 m0, s99, 0x1c000
	s_nop 0
	global_load_lds_dwordx4 v210, s[44:45]
	s_add_u32 m0, s99, 0x1e000
	s_nop 0
	global_load_lds_dwordx4 v211, s[44:45]
	s_add_u32 s44, s44, 0x80
	s_addc_u32 s45, s45, 0
	s_waitcnt vmcnt(6)
	s_barrier
	s_mov_b32 s101, 15
.Lg8_p4_loop:
	ds_read_b128 v[160:163], v197 offset:0
	ds_read_b128 v[164:167], v199 offset:0
	ds_read_b128 v[168:171], v197 offset:2048
	ds_read_b128 v[172:175], v199 offset:2048
	ds_read_b128 v[128:131], v184 offset:0
	ds_read_b128 v[132:135], v187 offset:0
	ds_read_b128 v[136:139], v184 offset:2048
	ds_read_b128 v[140:143], v187 offset:2048
	ds_read_b128 v[144:147], v184 offset:4096
	ds_read_b128 v[148:151], v187 offset:4096
	ds_read_b128 v[152:155], v184 offset:6144
	ds_read_b128 v[156:159], v187 offset:6144
	s_add_u32 m0, s99, 0x14000
	s_nop 0
	global_load_lds_dwordx4 v203, s[46:47]
	s_add_u32 m0, s99, 0x16000
	s_nop 0
	global_load_lds_dwordx4 v204, s[46:47]
	s_add_u32 s46, s46, 0x80
	s_addc_u32 s47, s47, 0
	s_waitcnt lgkmcnt(8)
	s_barrier
	s_waitcnt lgkmcnt(0)
	s_setprio 1
	v_mfma_f32_16x16x32_bf16 v[112:115], v[128:131], v[160:163], v[112:115]
	v_mfma_f32_16x16x32_bf16 v[112:115], v[132:135], v[164:167], v[112:115]
	v_mfma_f32_16x16x32_bf16 v[116:119], v[128:131], v[168:171], v[116:119]
	v_mfma_f32_16x16x32_bf16 v[116:119], v[132:135], v[172:175], v[116:119]
	v_mfma_f32_16x16x32_bf16 v[120:123], v[136:139], v[160:163], v[120:123]
	v_mfma_f32_16x16x32_bf16 v[120:123], v[140:143], v[164:167], v[120:123]
	v_mfma_f32_16x16x32_bf16 v[124:127], v[136:139], v[168:171], v[124:127]
	v_mfma_f32_16x16x32_bf16 v[124:127], v[140:143], v[172:175], v[124:127]
	v_mfma_f32_16x16x32_bf16 v[96:99], v[144:147], v[160:163], v[96:99]
	v_mfma_f32_16x16x32_bf16 v[96:99], v[148:151], v[164:167], v[96:99]
	v_mfma_f32_16x16x32_bf16 v[100:103], v[144:147], v[168:171], v[100:103]
	v_mfma_f32_16x16x32_bf16 v[100:103], v[148:151], v[172:175], v[100:103]
	v_mfma_f32_16x16x32_bf16 v[104:107], v[152:155], v[160:163], v[104:107]
	v_mfma_f32_16x16x32_bf16 v[104:107], v[156:159], v[164:167], v[104:107]
	v_mfma_f32_16x16x32_bf16 v[108:111], v[152:155], v[168:171], v[108:111]
	v_mfma_f32_16x16x32_bf16 v[108:111], v[156:159], v[172:175], v[108:111]
	s_setprio 0
	s_barrier
	ds_read_b128 v[176:179], v197 offset:16384
	ds_read_b128 v[180:183], v199 offset:16384
	ds_read_b128 v[188:191], v197 offset:18432
	ds_read_b128 v[192:195], v199 offset:18432
	s_add_u32 m0, s99, 0x8000
	s_nop 0
	global_load_lds_dwordx4 v205, s[44:45]
	s_add_u32 m0, s99, 0xa000
	s_nop 0
	global_load_lds_dwordx4 v206, s[44:45]
	s_barrier
	s_waitcnt lgkmcnt(0)
	s_setprio 1
	v_mfma_f32_16x16x32_bf16 v[48:51], v[128:131], v[176:179], v[48:51]
	v_mfma_f32_16x16x32_bf16 v[48:51], v[132:135], v[180:183], v[48:51]
	v_mfma_f32_16x16x32_bf16 v[52:55], v[128:131], v[188:191], v[52:55]
	v_mfma_f32_16x16x32_bf16 v[52:55], v[132:135], v[192:195], v[52:55]
	v_mfma_f32_16x16x32_bf16 v[56:59], v[136:139], v[176:179], v[56:59]
	v_mfma_f32_16x16x32_bf16 v[56:59], v[140:143], v[180:183], v[56:59]
	v_mfma_f32_16x16x32_bf16 v[60:63], v[136:139], v[188:191], v[60:63]
	v_mfma_f32_16x16x32_bf16 v[60:63], v[140:143], v[192:195], v[60:63]
	v_mfma_f32_16x16x32_bf16 v[32:35], v[144:147], v[176:179], v[32:35]
	v_mfma_f32_16x16x32_bf16 v[32:35], v[148:151], v[180:183], v[32:35]
	v_mfma_f32_16x16x32_bf16 v[36:39], v[144:147], v[188:191], v[36:39]
	v_mfma_f32_16x16x32_bf16 v[36:39], v[148:151], v[192:195], v[36:39]
	v_mfma_f32_16x16x32_bf16 v[40:43], v[152:155], v[176:179], v[40:43]
	v_mfma_f32_16x16x32_bf16 v[40:43], v[156:159], v[180:183], v[40:43]
	v_mfma_f32_16x16x32_bf16 v[44:47], v[152:155], v[188:191], v[44:47]
	v_mfma_f32_16x16x32_bf16 v[44:47], v[156:159], v[192:195], v[44:47]
	s_setprio 0
	s_barrier
	ds_read_b128 v[128:131], v184 offset:16384
	ds_read_b128 v[132:135], v187 offset:16384
	ds_read_b128 v[136:139], v184 offset:18432
	ds_read_b128 v[140:143], v187 offset:18432
	ds_read_b128 v[144:147], v184 offset:20480
	ds_read_b128 v[148:151], v187 offset:20480
	ds_read_b128 v[152:155], v184 offset:22528
	ds_read_b128 v[156:159], v187 offset:22528
	s_add_u32 m0, s99, 0x0
	s_nop 0
	global_load_lds_dwordx4 v201, s[46:47]
	s_add_u32 m0, s99, 0x2000
	s_nop 0
	global_load_lds_dwordx4 v202, s[46:47]
	s_barrier
	s_waitcnt lgkmcnt(0)
	s_setprio 1
	v_mfma_f32_16x16x32_bf16 v[64:67], v[128:131], v[160:163], v[64:67]
	v_mfma_f32_16x16x32_bf16 v[64:67], v[132:135], v[164:167], v[64:67]
	v_mfma_f32_16x16x32_bf16 v[68:71], v[128:131], v[168:171], v[68:71]
	v_mfma_f32_16x16x32_bf16 v[68:71], v[132:135], v[172:175], v[68:71]
	v_mfma_f32_16x16x32_bf16 v[72:75], v[136:139], v[160:163], v[72:75]
	v_mfma_f32_16x16x32_bf16 v[72:75], v[140:143], v[164:167], v[72:75]
	v_mfma_f32_16x16x32_bf16 v[76:79], v[136:139], v[168:171], v[76:79]
	v_mfma_f32_16x16x32_bf16 v[76:79], v[140:143], v[172:175], v[76:79]
	v_mfma_f32_16x16x32_bf16 v[80:83], v[144:147], v[160:163], v[80:83]
	v_mfma_f32_16x16x32_bf16 v[80:83], v[148:151], v[164:167], v[80:83]
	v_mfma_f32_16x16x32_bf16 v[84:87], v[144:147], v[168:171], v[84:87]
	v_mfma_f32_16x16x32_bf16 v[84:87], v[148:151], v[172:175], v[84:87]
	v_mfma_f32_16x16x32_bf16 v[88:91], v[152:155], v[160:163], v[88:91]
	v_mfma_f32_16x16x32_bf16 v[88:91], v[156:159], v[164:167], v[88:91]
	v_mfma_f32_16x16x32_bf16 v[92:95], v[152:155], v[168:171], v[92:95]
	v_mfma_f32_16x16x32_bf16 v[92:95], v[156:159], v[172:175], v[92:95]
	s_setprio 0
	s_barrier
	s_add_u32 m0, s99, 0xc000
	s_nop 0
	global_load_lds_dwordx4 v210, s[44:45]
	s_add_u32 m0, s99, 0xe000
	s_nop 0
	global_load_lds_dwordx4 v211, s[44:45]
	s_add_u32 s44, s44, 0x80
	s_addc_u32 s45, s45, 0
	s_waitcnt vmcnt(6)
	s_barrier
	s_setprio 1
	v_mfma_f32_16x16x32_bf16 v[16:19], v[128:131], v[176:179], v[16:19]
	v_mfma_f32_16x16x32_bf16 v[16:19], v[132:135], v[180:183], v[16:19]
	v_mfma_f32_16x16x32_bf16 v[20:23], v[128:131], v[188:191], v[20:23]
	v_mfma_f32_16x16x32_bf16 v[20:23], v[132:135], v[192:195], v[20:23]
	v_mfma_f32_16x16x32_bf16 v[24:27], v[136:139], v[176:179], v[24:27]
	v_mfma_f32_16x16x32_bf16 v[24:27], v[140:143], v[180:183], v[24:27]
	v_mfma_f32_16x16x32_bf16 v[28:31], v[136:139], v[188:191], v[28:31]
	v_mfma_f32_16x16x32_bf16 v[28:31], v[140:143], v[192:195], v[28:31]
	v_mfma_f32_16x16x32_bf16 v[0:3], v[144:147], v[176:179], v[0:3]
	v_mfma_f32_16x16x32_bf16 v[0:3], v[148:151], v[180:183], v[0:3]
	v_mfma_f32_16x16x32_bf16 v[4:7], v[144:147], v[188:191], v[4:7]
	v_mfma_f32_16x16x32_bf16 v[4:7], v[148:151], v[192:195], v[4:7]
	v_mfma_f32_16x16x32_bf16 v[8:11], v[152:155], v[176:179], v[8:11]
	v_mfma_f32_16x16x32_bf16 v[8:11], v[156:159], v[180:183], v[8:11]
	v_mfma_f32_16x16x32_bf16 v[12:15], v[152:155], v[188:191], v[12:15]
	v_mfma_f32_16x16x32_bf16 v[12:15], v[156:159], v[192:195], v[12:15]
	s_setprio 0
	s_barrier
	ds_read_b128 v[160:163], v198 offset:0
	ds_read_b128 v[164:167], v200 offset:0
	ds_read_b128 v[168:171], v198 offset:2048
	ds_read_b128 v[172:175], v200 offset:2048
	ds_read_b128 v[128:131], v186 offset:0
	ds_read_b128 v[132:135], v196 offset:0
	ds_read_b128 v[136:139], v186 offset:2048
	ds_read_b128 v[140:143], v196 offset:2048
	ds_read_b128 v[144:147], v186 offset:4096
	ds_read_b128 v[148:151], v196 offset:4096
	ds_read_b128 v[152:155], v186 offset:6144
	ds_read_b128 v[156:159], v196 offset:6144
	s_add_u32 m0, s99, 0x4000
	s_nop 0
	global_load_lds_dwordx4 v203, s[46:47]
	s_add_u32 m0, s99, 0x6000
	s_nop 0
	global_load_lds_dwordx4 v204, s[46:47]
	s_add_u32 s46, s46, 0x80
	s_addc_u32 s47, s47, 0
	s_waitcnt lgkmcnt(8)
	s_barrier
	s_waitcnt lgkmcnt(0)
	s_setprio 1
	v_mfma_f32_16x16x32_bf16 v[112:115], v[128:131], v[160:163], v[112:115]
	v_mfma_f32_16x16x32_bf16 v[112:115], v[132:135], v[164:167], v[112:115]
	v_mfma_f32_16x16x32_bf16 v[116:119], v[128:131], v[168:171], v[116:119]
	v_mfma_f32_16x16x32_bf16 v[116:119], v[132:135], v[172:175], v[116:119]
	v_mfma_f32_16x16x32_bf16 v[120:123], v[136:139], v[160:163], v[120:123]
	v_mfma_f32_16x16x32_bf16 v[120:123], v[140:143], v[164:167], v[120:123]
	v_mfma_f32_16x16x32_bf16 v[124:127], v[136:139], v[168:171], v[124:127]
	v_mfma_f32_16x16x32_bf16 v[124:127], v[140:143], v[172:175], v[124:127]
	v_mfma_f32_16x16x32_bf16 v[96:99], v[144:147], v[160:163], v[96:99]
	v_mfma_f32_16x16x32_bf16 v[96:99], v[148:151], v[164:167], v[96:99]
	v_mfma_f32_16x16x32_bf16 v[100:103], v[144:147], v[168:171], v[100:103]
	v_mfma_f32_16x16x32_bf16 v[100:103], v[148:151], v[172:175], v[100:103]
	v_mfma_f32_16x16x32_bf16 v[104:107], v[152:155], v[160:163], v[104:107]
	v_mfma_f32_16x16x32_bf16 v[104:107], v[156:159], v[164:167], v[104:107]
	v_mfma_f32_16x16x32_bf16 v[108:111], v[152:155], v[168:171], v[108:111]
	v_mfma_f32_16x16x32_bf16 v[108:111], v[156:159], v[172:175], v[108:111]
	s_setprio 0
	s_barrier
	ds_read_b128 v[176:179], v198 offset:16384
	ds_read_b128 v[180:183], v200 offset:16384
	ds_read_b128 v[188:191], v198 offset:18432
	ds_read_b128 v[192:195], v200 offset:18432
	s_add_u32 m0, s99, 0x18000
	s_nop 0
	global_load_lds_dwordx4 v205, s[44:45]
	s_add_u32 m0, s99, 0x1a000
	s_nop 0
	global_load_lds_dwordx4 v206, s[44:45]
	s_barrier
	s_waitcnt lgkmcnt(0)
	s_setprio 1
	v_mfma_f32_16x16x32_bf16 v[48:51], v[128:131], v[176:179], v[48:51]
	v_mfma_f32_16x16x32_bf16 v[48:51], v[132:135], v[180:183], v[48:51]
	v_mfma_f32_16x16x32_bf16 v[52:55], v[128:131], v[188:191], v[52:55]
	v_mfma_f32_16x16x32_bf16 v[52:55], v[132:135], v[192:195], v[52:55]
	v_mfma_f32_16x16x32_bf16 v[56:59], v[136:139], v[176:179], v[56:59]
	v_mfma_f32_16x16x32_bf16 v[56:59], v[140:143], v[180:183], v[56:59]
	v_mfma_f32_16x16x32_bf16 v[60:63], v[136:139], v[188:191], v[60:63]
	v_mfma_f32_16x16x32_bf16 v[60:63], v[140:143], v[192:195], v[60:63]
	v_mfma_f32_16x16x32_bf16 v[32:35], v[144:147], v[176:179], v[32:35]
	v_mfma_f32_16x16x32_bf16 v[32:35], v[148:151], v[180:183], v[32:35]
	v_mfma_f32_16x16x32_bf16 v[36:39], v[144:147], v[188:191], v[36:39]
	v_mfma_f32_16x16x32_bf16 v[36:39], v[148:151], v[192:195], v[36:39]
	v_mfma_f32_16x16x32_bf16 v[40:43], v[152:155], v[176:179], v[40:43]
	v_mfma_f32_16x16x32_bf16 v[40:43], v[156:159], v[180:183], v[40:43]
	v_mfma_f32_16x16x32_bf16 v[44:47], v[152:155], v[188:191], v[44:47]
	v_mfma_f32_16x16x32_bf16 v[44:47], v[156:159], v[192:195], v[44:47]
	s_setprio 0
	s_barrier
	ds_read_b128 v[128:131], v186 offset:16384
	ds_read_b128 v[132:135], v196 offset:16384
	ds_read_b128 v[136:139], v186 offset:18432
	ds_read_b128 v[140:143], v196 offset:18432
	ds_read_b128 v[144:147], v186 offset:20480
	ds_read_b128 v[148:151], v196 offset:20480
	ds_read_b128 v[152:155], v186 offset:22528
	ds_read_b128 v[156:159], v196 offset:22528
	s_add_u32 m0, s99, 0x10000
	s_nop 0
	global_load_lds_dwordx4 v201, s[46:47]
	s_add_u32 m0, s99, 0x12000
	s_nop 0
	global_load_lds_dwordx4 v202, s[46:47]
	s_barrier
	s_waitcnt lgkmcnt(0)
	s_setprio 1
	v_mfma_f32_16x16x32_bf16 v[64:67], v[128:131], v[160:163], v[64:67]
	v_mfma_f32_16x16x32_bf16 v[64:67], v[132:135], v[164:167], v[64:67]
	v_mfma_f32_16x16x32_bf16 v[68:71], v[128:131], v[168:171], v[68:71]
	v_mfma_f32_16x16x32_bf16 v[68:71], v[132:135], v[172:175], v[68:71]
	v_mfma_f32_16x16x32_bf16 v[72:75], v[136:139], v[160:163], v[72:75]
	v_mfma_f32_16x16x32_bf16 v[72:75], v[140:143], v[164:167], v[72:75]
	v_mfma_f32_16x16x32_bf16 v[76:79], v[136:139], v[168:171], v[76:79]
	v_mfma_f32_16x16x32_bf16 v[76:79], v[140:143], v[172:175], v[76:79]
	v_mfma_f32_16x16x32_bf16 v[80:83], v[144:147], v[160:163], v[80:83]
	v_mfma_f32_16x16x32_bf16 v[80:83], v[148:151], v[164:167], v[80:83]
	v_mfma_f32_16x16x32_bf16 v[84:87], v[144:147], v[168:171], v[84:87]
	v_mfma_f32_16x16x32_bf16 v[84:87], v[148:151], v[172:175], v[84:87]
	v_mfma_f32_16x16x32_bf16 v[88:91], v[152:155], v[160:163], v[88:91]
	v_mfma_f32_16x16x32_bf16 v[88:91], v[156:159], v[164:167], v[88:91]
	v_mfma_f32_16x16x32_bf16 v[92:95], v[152:155], v[168:171], v[92:95]
	v_mfma_f32_16x16x32_bf16 v[92:95], v[156:159], v[172:175], v[92:95]
	s_setprio 0
	s_barrier
	s_add_u32 m0, s99, 0x1c000
	s_nop 0
	global_load_lds_dwordx4 v210, s[44:45]
	s_add_u32 m0, s99, 0x1e000
	s_nop 0
	global_load_lds_dwordx4 v211, s[44:45]
	s_add_u32 s44, s44, 0x80
	s_addc_u32 s45, s45, 0
	s_waitcnt vmcnt(6)
	s_barrier
	s_setprio 1
	v_mfma_f32_16x16x32_bf16 v[16:19], v[128:131], v[176:179], v[16:19]
	v_mfma_f32_16x16x32_bf16 v[16:19], v[132:135], v[180:183], v[16:19]
	v_mfma_f32_16x16x32_bf16 v[20:23], v[128:131], v[188:191], v[20:23]
	v_mfma_f32_16x16x32_bf16 v[20:23], v[132:135], v[192:195], v[20:23]
	v_mfma_f32_16x16x32_bf16 v[24:27], v[136:139], v[176:179], v[24:27]
	v_mfma_f32_16x16x32_bf16 v[24:27], v[140:143], v[180:183], v[24:27]
	v_mfma_f32_16x16x32_bf16 v[28:31], v[136:139], v[188:191], v[28:31]
	v_mfma_f32_16x16x32_bf16 v[28:31], v[140:143], v[192:195], v[28:31]
	v_mfma_f32_16x16x32_bf16 v[0:3], v[144:147], v[176:179], v[0:3]
	v_mfma_f32_16x16x32_bf16 v[0:3], v[148:151], v[180:183], v[0:3]
	v_mfma_f32_16x16x32_bf16 v[4:7], v[144:147], v[188:191], v[4:7]
	v_mfma_f32_16x16x32_bf16 v[4:7], v[148:151], v[192:195], v[4:7]
	v_mfma_f32_16x16x32_bf16 v[8:11], v[152:155], v[176:179], v[8:11]
	v_mfma_f32_16x16x32_bf16 v[8:11], v[156:159], v[180:183], v[8:11]
	v_mfma_f32_16x16x32_bf16 v[12:15], v[152:155], v[188:191], v[12:15]
	v_mfma_f32_16x16x32_bf16 v[12:15], v[156:159], v[192:195], v[12:15]
	s_setprio 0
	s_barrier
	s_sub_u32 s101, s101, 1
	s_cmp_lg_u32 s101, 0
	s_cbranch_scc1 .Lg8_p4_loop
	ds_read_b128 v[160:163], v197 offset:0
	ds_read_b128 v[164:167], v199 offset:0
	ds_read_b128 v[168:171], v197 offset:2048
	ds_read_b128 v[172:175], v199 offset:2048
	ds_read_b128 v[128:131], v184 offset:0
	ds_read_b128 v[132:135], v187 offset:0
	ds_read_b128 v[136:139], v184 offset:2048
	ds_read_b128 v[140:143], v187 offset:2048
	ds_read_b128 v[144:147], v184 offset:4096
	ds_read_b128 v[148:151], v187 offset:4096
	ds_read_b128 v[152:155], v184 offset:6144
	ds_read_b128 v[156:159], v187 offset:6144
	s_add_u32 m0, s99, 0x14000
	s_nop 0
	global_load_lds_dwordx4 v203, s[46:47]
	s_add_u32 m0, s99, 0x16000
	s_nop 0
	global_load_lds_dwordx4 v204, s[46:47]
	s_add_u32 s46, s46, 0x80
	s_addc_u32 s47, s47, 0
	s_barrier
	s_waitcnt lgkmcnt(0)
	s_setprio 1
	v_mfma_f32_16x16x32_bf16 v[112:115], v[128:131], v[160:163], v[112:115]
	v_mfma_f32_16x16x32_bf16 v[112:115], v[132:135], v[164:167], v[112:115]
	v_mfma_f32_16x16x32_bf16 v[116:119], v[128:131], v[168:171], v[116:119]
	v_mfma_f32_16x16x32_bf16 v[116:119], v[132:135], v[172:175], v[116:119]
	v_mfma_f32_16x16x32_bf16 v[120:123], v[136:139], v[160:163], v[120:123]
	v_mfma_f32_16x16x32_bf16 v[120:123], v[140:143], v[164:167], v[120:123]
	v_mfma_f32_16x16x32_bf16 v[124:127], v[136:139], v[168:171], v[124:127]
	v_mfma_f32_16x16x32_bf16 v[124:127], v[140:143], v[172:175], v[124:127]
	v_mfma_f32_16x16x32_bf16 v[96:99], v[144:147], v[160:163], v[96:99]
	v_mfma_f32_16x16x32_bf16 v[96:99], v[148:151], v[164:167], v[96:99]
	v_mfma_f32_16x16x32_bf16 v[100:103], v[144:147], v[168:171], v[100:103]
	v_mfma_f32_16x16x32_bf16 v[100:103], v[148:151], v[172:175], v[100:103]
	v_mfma_f32_16x16x32_bf16 v[104:107], v[152:155], v[160:163], v[104:107]
	v_mfma_f32_16x16x32_bf16 v[104:107], v[156:159], v[164:167], v[104:107]
	v_mfma_f32_16x16x32_bf16 v[108:111], v[152:155], v[168:171], v[108:111]
	v_mfma_f32_16x16x32_bf16 v[108:111], v[156:159], v[172:175], v[108:111]
	s_setprio 0
	s_barrier
	ds_read_b128 v[176:179], v197 offset:16384
	ds_read_b128 v[180:183], v199 offset:16384
	ds_read_b128 v[188:191], v197 offset:18432
	ds_read_b128 v[192:195], v199 offset:18432
	s_barrier
	s_waitcnt lgkmcnt(0)
	s_setprio 1
	v_mfma_f32_16x16x32_bf16 v[48:51], v[128:131], v[176:179], v[48:51]
	v_mfma_f32_16x16x32_bf16 v[48:51], v[132:135], v[180:183], v[48:51]
	v_mfma_f32_16x16x32_bf16 v[52:55], v[128:131], v[188:191], v[52:55]
	v_mfma_f32_16x16x32_bf16 v[52:55], v[132:135], v[192:195], v[52:55]
	v_mfma_f32_16x16x32_bf16 v[56:59], v[136:139], v[176:179], v[56:59]
	v_mfma_f32_16x16x32_bf16 v[56:59], v[140:143], v[180:183], v[56:59]
	v_mfma_f32_16x16x32_bf16 v[60:63], v[136:139], v[188:191], v[60:63]
	v_mfma_f32_16x16x32_bf16 v[60:63], v[140:143], v[192:195], v[60:63]
	v_mfma_f32_16x16x32_bf16 v[32:35], v[144:147], v[176:179], v[32:35]
	v_mfma_f32_16x16x32_bf16 v[32:35], v[148:151], v[180:183], v[32:35]
	v_mfma_f32_16x16x32_bf16 v[36:39], v[144:147], v[188:191], v[36:39]
	v_mfma_f32_16x16x32_bf16 v[36:39], v[148:151], v[192:195], v[36:39]
	v_mfma_f32_16x16x32_bf16 v[40:43], v[152:155], v[176:179], v[40:43]
	v_mfma_f32_16x16x32_bf16 v[40:43], v[156:159], v[180:183], v[40:43]
	v_mfma_f32_16x16x32_bf16 v[44:47], v[152:155], v[188:191], v[44:47]
	v_mfma_f32_16x16x32_bf16 v[44:47], v[156:159], v[192:195], v[44:47]
	s_setprio 0
	s_barrier
	ds_read_b128 v[128:131], v184 offset:16384
	ds_read_b128 v[132:135], v187 offset:16384
	ds_read_b128 v[136:139], v184 offset:18432
	ds_read_b128 v[140:143], v187 offset:18432
	ds_read_b128 v[144:147], v184 offset:20480
	ds_read_b128 v[148:151], v187 offset:20480
	ds_read_b128 v[152:155], v184 offset:22528
	ds_read_b128 v[156:159], v187 offset:22528
	s_waitcnt vmcnt(4)
	s_barrier
	s_waitcnt lgkmcnt(0)
	s_setprio 1
	v_mfma_f32_16x16x32_bf16 v[64:67], v[128:131], v[160:163], v[64:67]
	v_mfma_f32_16x16x32_bf16 v[64:67], v[132:135], v[164:167], v[64:67]
	v_mfma_f32_16x16x32_bf16 v[68:71], v[128:131], v[168:171], v[68:71]
	v_mfma_f32_16x16x32_bf16 v[68:71], v[132:135], v[172:175], v[68:71]
	v_mfma_f32_16x16x32_bf16 v[72:75], v[136:139], v[160:163], v[72:75]
	v_mfma_f32_16x16x32_bf16 v[72:75], v[140:143], v[164:167], v[72:75]
	v_mfma_f32_16x16x32_bf16 v[76:79], v[136:139], v[168:171], v[76:79]
	v_mfma_f32_16x16x32_bf16 v[76:79], v[140:143], v[172:175], v[76:79]
	v_mfma_f32_16x16x32_bf16 v[80:83], v[144:147], v[160:163], v[80:83]
	v_mfma_f32_16x16x32_bf16 v[80:83], v[148:151], v[164:167], v[80:83]
	v_mfma_f32_16x16x32_bf16 v[84:87], v[144:147], v[168:171], v[84:87]
	v_mfma_f32_16x16x32_bf16 v[84:87], v[148:151], v[172:175], v[84:87]
	v_mfma_f32_16x16x32_bf16 v[88:91], v[152:155], v[160:163], v[88:91]
	v_mfma_f32_16x16x32_bf16 v[88:91], v[156:159], v[164:167], v[88:91]
	v_mfma_f32_16x16x32_bf16 v[92:95], v[152:155], v[168:171], v[92:95]
	v_mfma_f32_16x16x32_bf16 v[92:95], v[156:159], v[172:175], v[92:95]
	s_setprio 0
	s_setprio 1
	v_mfma_f32_16x16x32_bf16 v[16:19], v[128:131], v[176:179], v[16:19]
	v_mfma_f32_16x16x32_bf16 v[16:19], v[132:135], v[180:183], v[16:19]
	v_mfma_f32_16x16x32_bf16 v[20:23], v[128:131], v[188:191], v[20:23]
	v_mfma_f32_16x16x32_bf16 v[20:23], v[132:135], v[192:195], v[20:23]
	v_mfma_f32_16x16x32_bf16 v[24:27], v[136:139], v[176:179], v[24:27]
	v_mfma_f32_16x16x32_bf16 v[24:27], v[140:143], v[180:183], v[24:27]
	v_mfma_f32_16x16x32_bf16 v[28:31], v[136:139], v[188:191], v[28:31]
	v_mfma_f32_16x16x32_bf16 v[28:31], v[140:143], v[192:195], v[28:31]
	v_mfma_f32_16x16x32_bf16 v[0:3], v[144:147], v[176:179], v[0:3]
	v_mfma_f32_16x16x32_bf16 v[0:3], v[148:151], v[180:183], v[0:3]
	v_mfma_f32_16x16x32_bf16 v[4:7], v[144:147], v[188:191], v[4:7]
	v_mfma_f32_16x16x32_bf16 v[4:7], v[148:151], v[192:195], v[4:7]
	v_mfma_f32_16x16x32_bf16 v[8:11], v[152:155], v[176:179], v[8:11]
	v_mfma_f32_16x16x32_bf16 v[8:11], v[156:159], v[180:183], v[8:11]
	v_mfma_f32_16x16x32_bf16 v[12:15], v[152:155], v[188:191], v[12:15]
	v_mfma_f32_16x16x32_bf16 v[12:15], v[156:159], v[192:195], v[12:15]
	s_setprio 0
	s_barrier
	ds_read_b128 v[160:163], v198 offset:0
	ds_read_b128 v[164:167], v200 offset:0
	ds_read_b128 v[168:171], v198 offset:2048
	ds_read_b128 v[172:175], v200 offset:2048
	ds_read_b128 v[128:131], v186 offset:0
	ds_read_b128 v[132:135], v196 offset:0
	ds_read_b128 v[136:139], v186 offset:2048
	ds_read_b128 v[140:143], v196 offset:2048
	ds_read_b128 v[144:147], v186 offset:4096
	ds_read_b128 v[148:151], v196 offset:4096
	ds_read_b128 v[152:155], v186 offset:6144
	ds_read_b128 v[156:159], v196 offset:6144
	s_waitcnt vmcnt(2)
	s_barrier
	s_waitcnt lgkmcnt(0)
	s_setprio 1
	v_mfma_f32_16x16x32_bf16 v[112:115], v[128:131], v[160:163], v[112:115]
	v_mfma_f32_16x16x32_bf16 v[112:115], v[132:135], v[164:167], v[112:115]
	v_mfma_f32_16x16x32_bf16 v[116:119], v[128:131], v[168:171], v[116:119]
	v_mfma_f32_16x16x32_bf16 v[116:119], v[132:135], v[172:175], v[116:119]
	v_mfma_f32_16x16x32_bf16 v[120:123], v[136:139], v[160:163], v[120:123]
	v_mfma_f32_16x16x32_bf16 v[120:123], v[140:143], v[164:167], v[120:123]
	v_mfma_f32_16x16x32_bf16 v[124:127], v[136:139], v[168:171], v[124:127]
	v_mfma_f32_16x16x32_bf16 v[124:127], v[140:143], v[172:175], v[124:127]
	v_mfma_f32_16x16x32_bf16 v[96:99], v[144:147], v[160:163], v[96:99]
	v_mfma_f32_16x16x32_bf16 v[96:99], v[148:151], v[164:167], v[96:99]
	v_mfma_f32_16x16x32_bf16 v[100:103], v[144:147], v[168:171], v[100:103]
	v_mfma_f32_16x16x32_bf16 v[100:103], v[148:151], v[172:175], v[100:103]
	v_mfma_f32_16x16x32_bf16 v[104:107], v[152:155], v[160:163], v[104:107]
	v_mfma_f32_16x16x32_bf16 v[104:107], v[156:159], v[164:167], v[104:107]
	v_mfma_f32_16x16x32_bf16 v[108:111], v[152:155], v[168:171], v[108:111]
	v_mfma_f32_16x16x32_bf16 v[108:111], v[156:159], v[172:175], v[108:111]
	s_setprio 0
	s_barrier
	ds_read_b128 v[176:179], v198 offset:16384
	ds_read_b128 v[180:183], v200 offset:16384
	ds_read_b128 v[188:191], v198 offset:18432
	ds_read_b128 v[192:195], v200 offset:18432
	s_waitcnt vmcnt(0)
	s_barrier
	s_waitcnt lgkmcnt(0)
	s_setprio 1
	v_mfma_f32_16x16x32_bf16 v[48:51], v[128:131], v[176:179], v[48:51]
	v_mfma_f32_16x16x32_bf16 v[48:51], v[132:135], v[180:183], v[48:51]
	v_mfma_f32_16x16x32_bf16 v[52:55], v[128:131], v[188:191], v[52:55]
	v_mfma_f32_16x16x32_bf16 v[52:55], v[132:135], v[192:195], v[52:55]
	v_mfma_f32_16x16x32_bf16 v[56:59], v[136:139], v[176:179], v[56:59]
	v_mfma_f32_16x16x32_bf16 v[56:59], v[140:143], v[180:183], v[56:59]
	v_mfma_f32_16x16x32_bf16 v[60:63], v[136:139], v[188:191], v[60:63]
	v_mfma_f32_16x16x32_bf16 v[60:63], v[140:143], v[192:195], v[60:63]
	v_mfma_f32_16x16x32_bf16 v[32:35], v[144:147], v[176:179], v[32:35]
	v_mfma_f32_16x16x32_bf16 v[32:35], v[148:151], v[180:183], v[32:35]
	v_mfma_f32_16x16x32_bf16 v[36:39], v[144:147], v[188:191], v[36:39]
	v_mfma_f32_16x16x32_bf16 v[36:39], v[148:151], v[192:195], v[36:39]
	v_mfma_f32_16x16x32_bf16 v[40:43], v[152:155], v[176:179], v[40:43]
	v_mfma_f32_16x16x32_bf16 v[40:43], v[156:159], v[180:183], v[40:43]
	v_mfma_f32_16x16x32_bf16 v[44:47], v[152:155], v[188:191], v[44:47]
	v_mfma_f32_16x16x32_bf16 v[44:47], v[156:159], v[192:195], v[44:47]
	s_setprio 0
	s_barrier
	ds_read_b128 v[128:131], v186 offset:16384
	ds_read_b128 v[132:135], v196 offset:16384
	ds_read_b128 v[136:139], v186 offset:18432
	ds_read_b128 v[140:143], v196 offset:18432
	ds_read_b128 v[144:147], v186 offset:20480
	ds_read_b128 v[148:151], v196 offset:20480
	ds_read_b128 v[152:155], v186 offset:22528
	ds_read_b128 v[156:159], v196 offset:22528
	s_barrier
	s_waitcnt lgkmcnt(0)
	s_setprio 1
	v_mfma_f32_16x16x32_bf16 v[64:67], v[128:131], v[160:163], v[64:67]
	v_mfma_f32_16x16x32_bf16 v[64:67], v[132:135], v[164:167], v[64:67]
	v_mfma_f32_16x16x32_bf16 v[68:71], v[128:131], v[168:171], v[68:71]
	v_mfma_f32_16x16x32_bf16 v[68:71], v[132:135], v[172:175], v[68:71]
	v_mfma_f32_16x16x32_bf16 v[72:75], v[136:139], v[160:163], v[72:75]
	v_mfma_f32_16x16x32_bf16 v[72:75], v[140:143], v[164:167], v[72:75]
	v_mfma_f32_16x16x32_bf16 v[76:79], v[136:139], v[168:171], v[76:79]
	v_mfma_f32_16x16x32_bf16 v[76:79], v[140:143], v[172:175], v[76:79]
	v_mfma_f32_16x16x32_bf16 v[80:83], v[144:147], v[160:163], v[80:83]
	v_mfma_f32_16x16x32_bf16 v[80:83], v[148:151], v[164:167], v[80:83]
	v_mfma_f32_16x16x32_bf16 v[84:87], v[144:147], v[168:171], v[84:87]
	v_mfma_f32_16x16x32_bf16 v[84:87], v[148:151], v[172:175], v[84:87]
	v_mfma_f32_16x16x32_bf16 v[88:91], v[152:155], v[160:163], v[88:91]
	v_mfma_f32_16x16x32_bf16 v[88:91], v[156:159], v[164:167], v[88:91]
	v_mfma_f32_16x16x32_bf16 v[92:95], v[152:155], v[168:171], v[92:95]
	v_mfma_f32_16x16x32_bf16 v[92:95], v[156:159], v[172:175], v[92:95]
	s_setprio 0
	s_setprio 1
	v_mfma_f32_16x16x32_bf16 v[16:19], v[128:131], v[176:179], v[16:19]
	v_mfma_f32_16x16x32_bf16 v[16:19], v[132:135], v[180:183], v[16:19]
	v_mfma_f32_16x16x32_bf16 v[20:23], v[128:131], v[188:191], v[20:23]
	v_mfma_f32_16x16x32_bf16 v[20:23], v[132:135], v[192:195], v[20:23]
	v_mfma_f32_16x16x32_bf16 v[24:27], v[136:139], v[176:179], v[24:27]
	v_mfma_f32_16x16x32_bf16 v[24:27], v[140:143], v[180:183], v[24:27]
	v_mfma_f32_16x16x32_bf16 v[28:31], v[136:139], v[188:191], v[28:31]
	v_mfma_f32_16x16x32_bf16 v[28:31], v[140:143], v[192:195], v[28:31]
	v_mfma_f32_16x16x32_bf16 v[0:3], v[144:147], v[176:179], v[0:3]
	v_mfma_f32_16x16x32_bf16 v[0:3], v[148:151], v[180:183], v[0:3]
	v_mfma_f32_16x16x32_bf16 v[4:7], v[144:147], v[188:191], v[4:7]
	v_mfma_f32_16x16x32_bf16 v[4:7], v[148:151], v[192:195], v[4:7]
	v_mfma_f32_16x16x32_bf16 v[8:11], v[152:155], v[176:179], v[8:11]
	v_mfma_f32_16x16x32_bf16 v[8:11], v[156:159], v[180:183], v[8:11]
	v_mfma_f32_16x16x32_bf16 v[12:15], v[152:155], v[188:191], v[12:15]
	v_mfma_f32_16x16x32_bf16 v[12:15], v[156:159], v[192:195], v[12:15]
	s_setprio 0
	s_barrier
	s_cmp_lg_u32 s100, 0
	s_cbranch_scc1 .Lg8_p4_eg1
	s_barrier
.Lg8_p4_eg1:
	s_nop 7
	s_nop 7
	v_permlane16_swap_b32_e32 v112, v116
	v_permlane16_swap_b32_e32 v113, v117
	v_permlane16_swap_b32_e32 v114, v118
	v_permlane16_swap_b32_e32 v115, v119
	v_permlane16_swap_b32_e32 v120, v124
	v_permlane16_swap_b32_e32 v121, v125
	v_permlane16_swap_b32_e32 v122, v126
	v_permlane16_swap_b32_e32 v123, v127
	v_permlane16_swap_b32_e32 v96, v100
	v_permlane16_swap_b32_e32 v97, v101
	v_permlane16_swap_b32_e32 v98, v102
	v_permlane16_swap_b32_e32 v99, v103
	v_permlane16_swap_b32_e32 v104, v108
	v_permlane16_swap_b32_e32 v105, v109
	v_permlane16_swap_b32_e32 v106, v110
	v_permlane16_swap_b32_e32 v107, v111
	v_permlane16_swap_b32_e32 v64, v68
	v_permlane16_swap_b32_e32 v65, v69
	v_permlane16_swap_b32_e32 v66, v70
	v_permlane16_swap_b32_e32 v67, v71
	v_permlane16_swap_b32_e32 v72, v76
	v_permlane16_swap_b32_e32 v73, v77
	v_permlane16_swap_b32_e32 v74, v78
	v_permlane16_swap_b32_e32 v75, v79
	v_permlane16_swap_b32_e32 v80, v84
	v_permlane16_swap_b32_e32 v81, v85
	v_permlane16_swap_b32_e32 v82, v86
	v_permlane16_swap_b32_e32 v83, v87
	v_permlane16_swap_b32_e32 v88, v92
	v_permlane16_swap_b32_e32 v89, v93
	v_permlane16_swap_b32_e32 v90, v94
	v_permlane16_swap_b32_e32 v91, v95
	v_permlane16_swap_b32_e32 v48, v52
	v_permlane16_swap_b32_e32 v49, v53
	v_permlane16_swap_b32_e32 v50, v54
	v_permlane16_swap_b32_e32 v51, v55
	v_permlane16_swap_b32_e32 v56, v60
	v_permlane16_swap_b32_e32 v57, v61
	v_permlane16_swap_b32_e32 v58, v62
	v_permlane16_swap_b32_e32 v59, v63
	v_permlane16_swap_b32_e32 v32, v36
	v_permlane16_swap_b32_e32 v33, v37
	v_permlane16_swap_b32_e32 v34, v38
	v_permlane16_swap_b32_e32 v35, v39
	v_permlane16_swap_b32_e32 v40, v44
	v_permlane16_swap_b32_e32 v41, v45
	v_permlane16_swap_b32_e32 v42, v46
	v_permlane16_swap_b32_e32 v43, v47
	v_permlane16_swap_b32_e32 v16, v20
	v_permlane16_swap_b32_e32 v17, v21
	v_permlane16_swap_b32_e32 v18, v22
	v_permlane16_swap_b32_e32 v19, v23
	v_permlane16_swap_b32_e32 v24, v28
	v_permlane16_swap_b32_e32 v25, v29
	v_permlane16_swap_b32_e32 v26, v30
	v_permlane16_swap_b32_e32 v27, v31
	v_permlane16_swap_b32_e32 v0, v4
	v_permlane16_swap_b32_e32 v1, v5
	v_permlane16_swap_b32_e32 v2, v6
	v_permlane16_swap_b32_e32 v3, v7
	v_permlane16_swap_b32_e32 v8, v12
	v_permlane16_swap_b32_e32 v9, v13
	v_permlane16_swap_b32_e32 v10, v14
	v_permlane16_swap_b32_e32 v11, v15
	s_nop 1
	s_ashr_i32 s2, s1, 5
	s_mul_hi_i32 s43, s2, 0x3000
	s_mulk_i32 s2, 0x3000
	v_mov_b32_e32 v194, v208
	s_add_u32 s2, s72, s2
	s_addc_u32 s43, s73, s43
	s_waitcnt vmcnt(1)
	v_lshrrev_b32_e32 v129, 3, v194
	s_lshl_b32 s44, s42, 10
	v_lshlrev_b32_e32 v128, 1, v194
	v_and_b32_e32 v129, 4, v129
	s_add_u32 s44, s2, s44
	v_and_or_b32 v195, v128, s36, v129
	s_addc_u32 s45, s43, 0
	v_lshlrev_b32_e32 v184, 2, v195
	s_waitcnt vmcnt(0)
	v_lshl_add_u64 v[132:133], s[44:45], 0, v[184:185]
	v_add_co_u32_e32 v128, vcc, s41, v132
	v_lshl_add_u64 v[190:191], v[132:133], 0, s[26:27]
	s_nop 0
	v_addc_co_u32_e32 v129, vcc, 0, v133, vcc
	global_load_dwordx4 v[128:131], v[128:129], off
	s_nop 0
	global_load_dwordx4 v[132:135], v[190:191], off offset:32
	global_load_dwordx4 v[136:139], v[190:191], off offset:64
	global_load_dwordx4 v[140:143], v[190:191], off offset:96
	global_load_dwordx4 v[144:147], v[190:191], off offset:128
	global_load_dwordx4 v[148:151], v[190:191], off offset:160
	global_load_dwordx4 v[152:155], v[190:191], off offset:192
	global_load_dwordx4 v[156:159], v[190:191], off offset:224
	global_load_dwordx4 v[160:163], v[190:191], off offset:256
	global_load_dwordx4 v[164:167], v[190:191], off offset:288
	global_load_dwordx4 v[168:171], v[190:191], off offset:320
	global_load_dwordx4 v[172:175], v[190:191], off offset:352
	global_load_dwordx4 v[176:179], v[190:191], off offset:384
	global_load_dwordx4 v[180:183], v[190:191], off offset:416
	global_load_dwordx4 v[186:189], v[190:191], off offset:448
	s_nop 0
	global_load_dwordx4 v[190:193], v[190:191], off offset:480
	v_and_b32_e32 v184, 31, v194
	v_lshrrev_b32_e32 v194, 1, v194
	v_and_or_b32 v184, v194, s35, v184
	v_mul_lo_u32 v184, v184, s40
	v_lshl_add_u32 v184, v195, 1, v184
	s_lshl_b64 s[28:29], s[28:29], 19
	s_add_u32 s2, s24, s28
	s_addc_u32 s29, s25, s29
	s_lshl_b32 s28, s42, 9
	s_add_u32 s28, s2, s28
	s_addc_u32 s29, s29, 0
	s_add_i32 s1, s1, s48
	s_cmpk_lt_i32 s1, 0x200
	s_waitcnt vmcnt(14)
	v_pk_mul_f32 v[116:117], v[116:117], v[132:133]
	v_pk_mul_f32 v[118:119], v[118:119], v[134:135]
	s_waitcnt vmcnt(13)
	v_pk_mul_f32 v[120:121], v[120:121], v[136:137]
	v_pk_mul_f32 v[122:123], v[122:123], v[138:139]
	s_waitcnt vmcnt(12)
	v_pk_mul_f32 v[124:125], v[124:125], v[140:141]
	v_pk_mul_f32 v[126:127], v[126:127], v[142:143]
	s_waitcnt vmcnt(11)
	v_pk_mul_f32 v[96:97], v[96:97], v[144:145]
	s_waitcnt vmcnt(7)
	v_pk_mul_f32 v[64:65], v[64:65], v[160:161]
	v_pk_mul_f32 v[66:67], v[66:67], v[162:163]
	s_waitcnt vmcnt(6)
	v_pk_mul_f32 v[68:69], v[68:69], v[164:165]
	v_pk_mul_f32 v[70:71], v[70:71], v[166:167]
	v_pk_mul_f32 v[98:99], v[98:99], v[146:147]
	v_pk_mul_f32 v[100:101], v[100:101], v[148:149]
	v_pk_mul_f32 v[112:113], v[112:113], v[128:129]
	v_pk_mul_f32 v[114:115], v[114:115], v[130:131]
	v_pk_mul_f32 v[102:103], v[102:103], v[150:151]
	v_pk_mul_f32 v[104:105], v[104:105], v[152:153]
	v_pk_mul_f32 v[106:107], v[106:107], v[154:155]
	v_pk_mul_f32 v[108:109], v[108:109], v[156:157]
	v_pk_mul_f32 v[110:111], v[110:111], v[158:159]
	v_cvt_pk_bf16_f32 v112, v112, v113
	v_cvt_pk_bf16_f32 v113, v114, v115
	v_cvt_pk_bf16_f32 v114, v116, v117
	v_cvt_pk_bf16_f32 v115, v118, v119
	v_cvt_pk_bf16_f32 v64, v64, v65
	v_cvt_pk_bf16_f32 v65, v66, v67
	v_cvt_pk_bf16_f32 v66, v68, v69
	v_cvt_pk_bf16_f32 v67, v70, v71
	v_cvt_pk_bf16_f32 v116, v120, v121
	v_cvt_pk_bf16_f32 v117, v122, v123
	v_cvt_pk_bf16_f32 v118, v124, v125
	v_cvt_pk_bf16_f32 v119, v126, v127
	v_cvt_pk_bf16_f32 v96, v96, v97
	v_cvt_pk_bf16_f32 v97, v98, v99
	v_cvt_pk_bf16_f32 v98, v100, v101
	v_cvt_pk_bf16_f32 v99, v102, v103
	v_cvt_pk_bf16_f32 v100, v104, v105
	v_cvt_pk_bf16_f32 v101, v106, v107
	v_cvt_pk_bf16_f32 v102, v108, v109
	v_cvt_pk_bf16_f32 v103, v110, v111
	ds_write2_b64 v184, v[112:113], v[114:115] offset1:2
	ds_write2_b64 v184, v[116:117], v[118:119] offset0:4 offset1:6
	ds_write2_b64 v184, v[96:97], v[98:99] offset0:8 offset1:10
	ds_write2_b64 v184, v[100:101], v[102:103] offset0:12 offset1:14
	ds_write2_b64 v184, v[64:65], v[66:67] offset0:16 offset1:18
	s_waitcnt vmcnt(5)
	v_pk_mul_f32 v[64:65], v[72:73], v[168:169]
	v_pk_mul_f32 v[66:67], v[74:75], v[170:171]
	v_cvt_pk_bf16_f32 v64, v64, v65
	v_cvt_pk_bf16_f32 v65, v66, v67
	s_waitcnt vmcnt(4)
	v_pk_mul_f32 v[66:67], v[76:77], v[172:173]
	v_pk_mul_f32 v[68:69], v[78:79], v[174:175]
	v_cvt_pk_bf16_f32 v66, v66, v67
	v_cvt_pk_bf16_f32 v67, v68, v69
	ds_write2_b64 v184, v[64:65], v[66:67] offset0:20 offset1:22
	s_waitcnt vmcnt(3)
	v_pk_mul_f32 v[64:65], v[80:81], v[176:177]
	v_pk_mul_f32 v[66:67], v[82:83], v[178:179]
	v_pk_mul_f32 v[48:49], v[48:49], v[128:129]
	v_pk_mul_f32 v[50:51], v[50:51], v[130:131]
	v_pk_mul_f32 v[32:33], v[32:33], v[144:145]
	v_pk_mul_f32 v[34:35], v[34:35], v[146:147]
	v_pk_mul_f32 v[16:17], v[16:17], v[160:161]
	v_pk_mul_f32 v[18:19], v[18:19], v[162:163]
	v_pk_mul_f32 v[0:1], v[0:1], v[176:177]
	v_pk_mul_f32 v[2:3], v[2:3], v[178:179]
	v_cvt_pk_bf16_f32 v64, v64, v65
	v_cvt_pk_bf16_f32 v65, v66, v67
	s_waitcnt vmcnt(2)
	v_pk_mul_f32 v[66:67], v[84:85], v[180:181]
	v_pk_mul_f32 v[68:69], v[86:87], v[182:183]
	v_cvt_pk_bf16_f32 v48, v48, v49
	v_cvt_pk_bf16_f32 v49, v50, v51
	v_pk_mul_f32 v[50:51], v[52:53], v[132:133]
	v_pk_mul_f32 v[52:53], v[54:55], v[134:135]
	v_cvt_pk_bf16_f32 v32, v32, v33
	v_cvt_pk_bf16_f32 v33, v34, v35
	v_pk_mul_f32 v[34:35], v[36:37], v[148:149]
	v_pk_mul_f32 v[36:37], v[38:39], v[150:151]
	v_cvt_pk_bf16_f32 v16, v16, v17
	v_cvt_pk_bf16_f32 v17, v18, v19
	v_pk_mul_f32 v[18:19], v[20:21], v[164:165]
	v_pk_mul_f32 v[20:21], v[22:23], v[166:167]
	v_cvt_pk_bf16_f32 v0, v0, v1
	v_cvt_pk_bf16_f32 v1, v2, v3
	v_pk_mul_f32 v[2:3], v[4:5], v[180:181]
	v_pk_mul_f32 v[4:5], v[6:7], v[182:183]
	v_cvt_pk_bf16_f32 v66, v66, v67
	v_cvt_pk_bf16_f32 v67, v68, v69
	v_cvt_pk_bf16_f32 v50, v50, v51
	v_cvt_pk_bf16_f32 v51, v52, v53
	v_add_u32_e32 v54, 0x4000, v184
	v_cvt_pk_bf16_f32 v34, v34, v35
	v_cvt_pk_bf16_f32 v35, v36, v37
	v_cvt_pk_bf16_f32 v18, v18, v19
	v_cvt_pk_bf16_f32 v19, v20, v21
	v_cvt_pk_bf16_f32 v2, v2, v3
	v_cvt_pk_bf16_f32 v3, v4, v5
	ds_write2_b64 v184, v[64:65], v[66:67] offset0:24 offset1:26
	s_waitcnt vmcnt(1)
	v_pk_mul_f32 v[64:65], v[88:89], v[186:187]
	v_pk_mul_f32 v[66:67], v[90:91], v[188:189]
	ds_write2_b64 v54, v[48:49], v[50:51] offset0:64 offset1:66
	v_pk_mul_f32 v[48:49], v[56:57], v[136:137]
	v_pk_mul_f32 v[50:51], v[58:59], v[138:139]
	ds_write2_b64 v54, v[32:33], v[34:35] offset0:72 offset1:74
	v_pk_mul_f32 v[32:33], v[40:41], v[152:153]
	v_pk_mul_f32 v[34:35], v[42:43], v[154:155]
	ds_write2_b64 v54, v[16:17], v[18:19] offset0:80 offset1:82
	v_pk_mul_f32 v[16:17], v[24:25], v[168:169]
	v_pk_mul_f32 v[18:19], v[26:27], v[170:171]
	ds_write2_b64 v54, v[0:1], v[2:3] offset0:88 offset1:90
	v_pk_mul_f32 v[0:1], v[8:9], v[186:187]
	v_pk_mul_f32 v[2:3], v[10:11], v[188:189]
	v_cvt_pk_bf16_f32 v64, v64, v65
	v_cvt_pk_bf16_f32 v65, v66, v67
	s_waitcnt vmcnt(0)
	v_pk_mul_f32 v[66:67], v[92:93], v[190:191]
	v_pk_mul_f32 v[68:69], v[94:95], v[192:193]
	v_cvt_pk_bf16_f32 v48, v48, v49
	v_cvt_pk_bf16_f32 v49, v50, v51
	v_pk_mul_f32 v[50:51], v[60:61], v[140:141]
	v_pk_mul_f32 v[52:53], v[62:63], v[142:143]
	v_cvt_pk_bf16_f32 v32, v32, v33
	v_cvt_pk_bf16_f32 v33, v34, v35
	v_pk_mul_f32 v[34:35], v[44:45], v[156:157]
	v_pk_mul_f32 v[36:37], v[46:47], v[158:159]
	v_cvt_pk_bf16_f32 v16, v16, v17
	v_cvt_pk_bf16_f32 v17, v18, v19
	v_pk_mul_f32 v[18:19], v[28:29], v[172:173]
	v_pk_mul_f32 v[20:21], v[30:31], v[174:175]
	v_cvt_pk_bf16_f32 v0, v0, v1
	v_cvt_pk_bf16_f32 v1, v2, v3
	v_pk_mul_f32 v[2:3], v[12:13], v[190:191]
	v_pk_mul_f32 v[4:5], v[14:15], v[192:193]
	v_cvt_pk_bf16_f32 v66, v66, v67
	v_cvt_pk_bf16_f32 v67, v68, v69
	v_cvt_pk_bf16_f32 v50, v50, v51
	v_cvt_pk_bf16_f32 v51, v52, v53
	v_cvt_pk_bf16_f32 v34, v34, v35
	v_cvt_pk_bf16_f32 v35, v36, v37
	v_cvt_pk_bf16_f32 v18, v18, v19
	v_cvt_pk_bf16_f32 v19, v20, v21
	v_cvt_pk_bf16_f32 v2, v2, v3
	v_cvt_pk_bf16_f32 v3, v4, v5
	v_mov_b32_e32 v14, v208
	ds_write2_b64 v184, v[64:65], v[66:67] offset0:28 offset1:30
	ds_write2_b64 v54, v[48:49], v[50:51] offset0:68 offset1:70
	ds_write2_b64 v54, v[32:33], v[34:35] offset0:76 offset1:78
	ds_write2_b64 v54, v[16:17], v[18:19] offset0:84 offset1:86
	ds_write2_b64 v54, v[0:1], v[2:3] offset0:92 offset1:94
	s_waitcnt lgkmcnt(0)
	v_lshlrev_b32_e32 v0, 4, v14
	v_ashrrev_i32_e32 v4, 5, v14
	v_and_b32_e32 v184, 0x1f0, v0
	v_ashrrev_i32_e32 v5, 31, v4
	v_lshl_add_u64 v[8:9], s[28:29], 0, v[184:185]
	v_mad_u64_u32 v[0:1], s[28:29], v4, s40, v[184:185]
	v_lshlrev_b64 v[4:5], 11, v[4:5]
	v_lshl_add_u64 v[10:11], v[8:9], 0, v[4:5]
	v_add_u32_e32 v4, 0x200, v14
	s_barrier
	ds_read_b128 v[0:3], v0
	v_ashrrev_i32_e32 v12, 5, v4
	v_mad_u64_u32 v[4:5], s[28:29], v12, s40, v[184:185]
	ds_read_b128 v[4:7], v4
	v_ashrrev_i32_e32 v13, 31, v12
	s_waitcnt lgkmcnt(1)
	global_store_dwordx4 v[10:11], v[0:3], off
	s_nop 1
	v_lshlrev_b64 v[0:1], 11, v[12:13]
	v_lshl_add_u64 v[0:1], v[8:9], 0, v[0:1]
	s_waitcnt lgkmcnt(0)
	global_store_dwordx4 v[0:1], v[4:7], off
	v_add_u32_e32 v0, 0x400, v14
	s_nop 0
	v_ashrrev_i32_e32 v4, 5, v0
	v_ashrrev_i32_e32 v5, 31, v4
	v_mad_u64_u32 v[0:1], s[28:29], v4, s40, v[184:185]
	v_lshlrev_b64 v[4:5], 11, v[4:5]
	v_lshl_add_u64 v[10:11], v[8:9], 0, v[4:5]
	v_add_u32_e32 v4, 0x600, v14
	ds_read_b128 v[0:3], v0
	v_ashrrev_i32_e32 v12, 5, v4
	v_mad_u64_u32 v[4:5], s[28:29], v12, s40, v[184:185]
	ds_read_b128 v[4:7], v4
	v_ashrrev_i32_e32 v13, 31, v12
	s_waitcnt lgkmcnt(1)
	global_store_dwordx4 v[10:11], v[0:3], off
	s_nop 1
	v_lshlrev_b64 v[0:1], 11, v[12:13]
	v_lshl_add_u64 v[0:1], v[8:9], 0, v[0:1]
	s_waitcnt lgkmcnt(0)
	global_store_dwordx4 v[0:1], v[4:7], off
	v_add_u32_e32 v0, 0x800, v14
	s_nop 0
	v_ashrrev_i32_e32 v4, 5, v0
	v_ashrrev_i32_e32 v5, 31, v4
	v_mad_u64_u32 v[0:1], s[28:29], v4, s40, v[184:185]
	v_lshlrev_b64 v[4:5], 11, v[4:5]
	v_lshl_add_u64 v[10:11], v[8:9], 0, v[4:5]
	v_add_u32_e32 v4, 0xa00, v14
	ds_read_b128 v[0:3], v0
	v_ashrrev_i32_e32 v12, 5, v4
	v_mad_u64_u32 v[4:5], s[28:29], v12, s40, v[184:185]
	ds_read_b128 v[4:7], v4
	v_ashrrev_i32_e32 v13, 31, v12
	s_waitcnt lgkmcnt(1)
	global_store_dwordx4 v[10:11], v[0:3], off
	s_nop 1
	v_lshlrev_b64 v[0:1], 11, v[12:13]
	v_lshl_add_u64 v[0:1], v[8:9], 0, v[0:1]
	s_waitcnt lgkmcnt(0)
	global_store_dwordx4 v[0:1], v[4:7], off
	v_add_u32_e32 v0, 0xc00, v14
	s_nop 0
	v_ashrrev_i32_e32 v4, 5, v0
	v_ashrrev_i32_e32 v5, 31, v4
	v_mad_u64_u32 v[0:1], s[28:29], v4, s40, v[184:185]
	v_lshlrev_b64 v[4:5], 11, v[4:5]
	v_lshl_add_u64 v[10:11], v[8:9], 0, v[4:5]
	v_add_u32_e32 v4, 0xe00, v14
	ds_read_b128 v[0:3], v0
	v_ashrrev_i32_e32 v12, 5, v4
	v_mad_u64_u32 v[4:5], s[28:29], v12, s40, v[184:185]
	ds_read_b128 v[4:7], v4
	v_ashrrev_i32_e32 v13, 31, v12
	s_waitcnt lgkmcnt(1)
	global_store_dwordx4 v[10:11], v[0:3], off
	s_nop 1
	v_lshlrev_b64 v[0:1], 11, v[12:13]
	v_lshl_add_u64 v[0:1], v[8:9], 0, v[0:1]
	s_waitcnt lgkmcnt(0)
	global_store_dwordx4 v[0:1], v[4:7], off
	v_add_u32_e32 v0, 0x1000, v14
	s_nop 0
	v_ashrrev_i32_e32 v4, 5, v0
	v_ashrrev_i32_e32 v5, 31, v4
	v_mad_u64_u32 v[0:1], s[28:29], v4, s40, v[184:185]
	v_lshlrev_b64 v[4:5], 11, v[4:5]
	v_lshl_add_u64 v[10:11], v[8:9], 0, v[4:5]
	v_add_u32_e32 v4, 0x1200, v14
	ds_read_b128 v[0:3], v0
	v_ashrrev_i32_e32 v12, 5, v4
	v_mad_u64_u32 v[4:5], s[28:29], v12, s40, v[184:185]
	ds_read_b128 v[4:7], v4
	v_ashrrev_i32_e32 v13, 31, v12
	s_waitcnt lgkmcnt(1)
	global_store_dwordx4 v[10:11], v[0:3], off
	s_nop 1
	v_lshlrev_b64 v[0:1], 11, v[12:13]
	v_lshl_add_u64 v[0:1], v[8:9], 0, v[0:1]
	s_waitcnt lgkmcnt(0)
	global_store_dwordx4 v[0:1], v[4:7], off
	v_add_u32_e32 v0, 0x1400, v14
	s_nop 0
	v_ashrrev_i32_e32 v4, 5, v0
	v_ashrrev_i32_e32 v5, 31, v4
	v_mad_u64_u32 v[0:1], s[28:29], v4, s40, v[184:185]
	v_lshlrev_b64 v[4:5], 11, v[4:5]
	v_lshl_add_u64 v[10:11], v[8:9], 0, v[4:5]
	v_add_u32_e32 v4, 0x1600, v14
	ds_read_b128 v[0:3], v0
	v_ashrrev_i32_e32 v12, 5, v4
	v_mad_u64_u32 v[4:5], s[28:29], v12, s40, v[184:185]
	ds_read_b128 v[4:7], v4
	v_ashrrev_i32_e32 v13, 31, v12
	s_waitcnt lgkmcnt(1)
	global_store_dwordx4 v[10:11], v[0:3], off
	s_nop 1
	v_lshlrev_b64 v[0:1], 11, v[12:13]
	v_lshl_add_u64 v[0:1], v[8:9], 0, v[0:1]
	s_waitcnt lgkmcnt(0)
	global_store_dwordx4 v[0:1], v[4:7], off
	v_add_u32_e32 v0, 0x1800, v14
	s_nop 0
	v_ashrrev_i32_e32 v4, 5, v0
	v_ashrrev_i32_e32 v5, 31, v4
	v_mad_u64_u32 v[0:1], s[28:29], v4, s40, v[184:185]
	v_lshlrev_b64 v[4:5], 11, v[4:5]
	v_lshl_add_u64 v[10:11], v[8:9], 0, v[4:5]
	v_add_u32_e32 v4, 0x1a00, v14
	ds_read_b128 v[0:3], v0
	v_ashrrev_i32_e32 v12, 5, v4
	v_mad_u64_u32 v[4:5], s[28:29], v12, s40, v[184:185]
	ds_read_b128 v[4:7], v4
	v_ashrrev_i32_e32 v13, 31, v12
	s_waitcnt lgkmcnt(1)
	global_store_dwordx4 v[10:11], v[0:3], off
	s_nop 1
	v_lshlrev_b64 v[0:1], 11, v[12:13]
	v_lshl_add_u64 v[0:1], v[8:9], 0, v[0:1]
	s_waitcnt lgkmcnt(0)
	global_store_dwordx4 v[0:1], v[4:7], off
	v_add_u32_e32 v0, 0x1c00, v14
	s_nop 0
	v_ashrrev_i32_e32 v4, 5, v0
	v_ashrrev_i32_e32 v5, 31, v4
	v_mad_u64_u32 v[0:1], s[28:29], v4, s40, v[184:185]
	v_lshlrev_b64 v[4:5], 11, v[4:5]
	v_lshl_add_u64 v[10:11], v[8:9], 0, v[4:5]
	v_add_u32_e32 v4, 0x1e00, v14
	ds_read_b128 v[0:3], v0
	v_ashrrev_i32_e32 v12, 5, v4
	v_mad_u64_u32 v[4:5], s[28:29], v12, s40, v[184:185]
	ds_read_b128 v[4:7], v4
	v_ashrrev_i32_e32 v13, 31, v12
	s_waitcnt lgkmcnt(1)
	global_store_dwordx4 v[10:11], v[0:3], off
	s_nop 1
	v_lshlrev_b64 v[0:1], 11, v[12:13]
	v_lshl_add_u64 v[0:1], v[8:9], 0, v[0:1]
	s_waitcnt lgkmcnt(0)
	global_store_dwordx4 v[0:1], v[4:7], off
	s_barrier
	s_cbranch_scc1 .LBB0_514

	.amdhsa_kernel _Z4megaILi0ELi10EEv6Params
		.amdhsa_group_segment_fixed_size 151552
		.amdhsa_private_segment_fixed_size 0
		.amdhsa_kernarg_size 424
		.amdhsa_user_sgpr_count 2
		.amdhsa_user_sgpr_dispatch_ptr 0
		.amdhsa_user_sgpr_queue_ptr 0
		.amdhsa_user_sgpr_kernarg_segment_ptr 1
		.amdhsa_user_sgpr_dispatch_id 0
		.amdhsa_user_sgpr_kernarg_preload_length 0
		.amdhsa_user_sgpr_kernarg_preload_offset 0
		.amdhsa_user_sgpr_private_segment_size 0
		.amdhsa_uses_dynamic_stack 0
		.amdhsa_enable_private_segment 0
		.amdhsa_system_sgpr_workgroup_id_x 1
		.amdhsa_system_sgpr_workgroup_id_y 0
		.amdhsa_system_sgpr_workgroup_id_z 0
		.amdhsa_system_sgpr_workgroup_info 0
		.amdhsa_system_vgpr_workitem_id 2
		.amdhsa_next_free_vgpr 256
		.amdhsa_next_free_sgpr 102
		.amdhsa_accum_offset 256
		.amdhsa_reserve_vcc 1
		.amdhsa_float_round_mode_32 0
		.amdhsa_float_round_mode_16_64 0
		.amdhsa_float_denorm_mode_32 3
		.amdhsa_float_denorm_mode_16_64 3
		.amdhsa_dx10_clamp 1
		.amdhsa_ieee_mode 1
		.amdhsa_fp16_overflow 0
		.amdhsa_tg_split 0
		.amdhsa_exception_fp_ieee_invalid_op 0
		.amdhsa_exception_fp_denorm_src 0
		.amdhsa_exception_fp_ieee_div_zero 0
		.amdhsa_exception_fp_ieee_overflow 0
		.amdhsa_exception_fp_ieee_underflow 0
		.amdhsa_exception_fp_ieee_inexact 0
		.amdhsa_exception_int_div_zero 0
	.end_amdhsa_kernel

amdhsa.kernels:
  - .agpr_count:     0
    .args:
      - .offset:         0
        .size:           168
        .value_kind:     by_value
      - .offset:         168
        .size:           4
        .value_kind:     hidden_block_count_x
      - .offset:         172
        .size:           4
        .value_kind:     hidden_block_count_y
      - .offset:         176
        .size:           4
        .value_kind:     hidden_block_count_z
      - .offset:         180
        .size:           2
        .value_kind:     hidden_group_size_x
      - .offset:         182
        .size:           2
        .value_kind:     hidden_group_size_y
      - .offset:         184
        .size:           2
        .value_kind:     hidden_group_size_z
      - .offset:         186
        .size:           2
        .value_kind:     hidden_remainder_x
      - .offset:         188
        .size:           2
        .value_kind:     hidden_remainder_y
      - .offset:         190
        .size:           2
        .value_kind:     hidden_remainder_z
      - .offset:         208
        .size:           8
        .value_kind:     hidden_global_offset_x
      - .offset:         216
        .size:           8
        .value_kind:     hidden_global_offset_y
      - .offset:         224
        .size:           8
        .value_kind:     hidden_global_offset_z
      - .offset:         232
        .size:           2
        .value_kind:     hidden_grid_dims
      - .offset:         256
        .size:           8
        .value_kind:     hidden_multigrid_sync_arg
    .group_segment_fixed_size: 151552
    .kernarg_segment_align: 8
    .kernarg_segment_size: 424
    .language:       OpenCL C
    .language_version:
      - 2
      - 0
    .max_flat_workgroup_size: 512
    .name:           _Z4megaILi0ELi10EEv6Params
    .private_segment_fixed_size: 0
    .sgpr_count:     108
    .sgpr_spill_count: 26
    .symbol:         _Z4megaILi0ELi10EEv6Params.kd
    .uniform_work_group_size: 1
    .uses_dynamic_stack: false
    .vgpr_count:     256
    .vgpr_spill_count: 0
    .wavefront_size: 64
